# speedup vs baseline: 1.0003x; 1.0003x over previous
; __device__ __forceinline__ void p2_prep(const Ctx& C0) {
;     ...
;         const int h = lane >> 3, d0 = (lane & 7) * 8;
;         float gqv[8], gkv[8];
; #pragma unroll
;         for (int j = 0; j < 8; ++j) { gqv[j] = gq[d0 + j] * QSCALE; gkv[j] = gk[d0 + j]; }
;         for (int tk0 = C.gw; tk0 < T; tk0 += 2 * C.NGW) {
;             u32x4 qv[2], kv[2];
; #pragma unroll
;             for (int u = 0; u < 2; ++u) {
;                 const int tk = (tk0 + u * C.NGW < T) ? tk0 + u * C.NGW : tk0;
;                 const bf16* pr = PROJ + (size_t)tk * 2048;
;                 qv[u] = *(const u32x4*)(pr + 512 + 8 * lane); kv[u] = *(const u32x4*)(pr + 1024 + 8 * lane);
.LBB0_379:
	s_cmpk_gt_i32 s0, 0x7fff
	s_cbranch_scc1 .LBB0_384
	v_and_b32_e32 v16, 56, v128
	v_lshlrev_b32_e32 v17, 2, v16
	global_load_dwordx4 v[8:11], v17, s[18:19]
	global_load_dwordx4 v[12:15], v17, s[18:19] offset:16
	global_load_dwordx4 v[0:3], v17, s[20:21] offset:16
	global_load_dwordx4 v[4:7], v17, s[20:21]
	v_mbcnt_hi_u32_b32 v20, -1, v197
	v_and_b32_e32 v21, 64, v20
	v_xor_b32_e32 v22, 1, v20
	v_add_u32_e32 v21, 64, v21
	v_xor_b32_e32 v23, 2, v20
	v_cmp_lt_i32_e32 vcc, v22, v21
	s_add_u32 s4, s78, 0xc000000
	v_xor_b32_e32 v24, 4, v20
	v_cndmask_b32_e32 v22, v20, v22, vcc
	v_cmp_lt_i32_e32 vcc, v23, v21
	s_addc_u32 s5, s79, 0
	v_mov_b32_e32 v19, 0
	v_cndmask_b32_e32 v23, v20, v23, vcc
	v_cmp_lt_i32_e32 vcc, v24, v21
	s_mov_b32 s24, 0x3e38aa3b
	v_lshlrev_b32_e32 v18, 4, v196
	s_add_u32 s16, s78, 0xe000000
	v_cndmask_b32_e32 v20, v20, v24, vcc
	v_lshrrev_b32_e32 v17, 3, v196
	s_mov_b32 s8, 0x3c800000
	s_mov_b32 s18, 0x800000
	v_lshl_add_u64 v[18:19], s[44:45], 0, v[18:19]
	s_addc_u32 s17, s79, 0
	s_lshl_b32 s19, s0, 6
	s_lshl_b32 s20, s22, 7
	s_lshl_b32 s21, s22, 6
	v_lshlrev_b32_e32 v29, 2, v22
	v_lshlrev_b32_e32 v30, 2, v23
	v_lshlrev_b32_e32 v31, 2, v20
	v_mov_b32_e32 v28, 0x358637bd
	s_waitcnt vmcnt(3)
	v_pk_mul_f32 v[20:21], v[8:9], s[24:25] op_sel_hi:[1,0]
	v_pk_mul_f32 v[22:23], v[10:11], s[24:25] op_sel_hi:[1,0]
	s_waitcnt vmcnt(2)
	v_pk_mul_f32 v[24:25], v[12:13], s[24:25] op_sel_hi:[1,0]
	v_pk_mul_f32 v[26:27], v[14:15], s[24:25] op_sel_hi:[1,0]
	s_ashr_i32 s1, s0, 31
	s_lshl_b64 s[48:49], s[0:1], 12
	v_lshl_add_u64 v[202:203], v[18:19], 0, s[48:49]
	global_load_dwordx4 v[206:209], v[202:203], off offset:1024 nt
	global_load_dwordx4 v[210:213], v[202:203], off offset:2048 nt
	global_load_dword v204, v[18:19], off
	global_load_dword v205, v[18:19], off
	s_branch .LBB0_382

; __device__ __forceinline__ unsigned pk2(float lo, float hi) { f32x2_t v = {lo, hi}; bf16x2_t b = __builtin_convertvector(v, bf16x2_t); return __builtin_bit_cast(unsigned, b); }
; __device__ __forceinline__ void p2_prep(const Ctx& C0) {
;     ...
;         for (int tk0 = C.gw; tk0 < T; tk0 += 2 * C.NGW) {
;             u32x4 qv[2], kv[2];
; #pragma unroll
;             for (int u = 0; u < 2; ++u) {
;                 const int tk = (tk0 + u * C.NGW < T) ? tk0 + u * C.NGW : tk0;
;                 const bf16* pr = PROJ + (size_t)tk * 2048;
;                 qv[u] = *(const u32x4*)(pr + 512 + 8 * lane); kv[u] = *(const u32x4*)(pr + 1024 + 8 * lane);
;             }
; #pragma unroll
;             for (int u = 0; u < 2; ++u) {
;                 const int tk = tk0 + u * C.NGW;
;                 if (tk < T) {
;                     const int b = tk >> 13, s = tk & 8191;
;                     float q[8] = {bflo(qv[u].x), bfhi(qv[u].x), bflo(qv[u].y), bfhi(qv[u].y), bflo(qv[u].z), bfhi(qv[u].z), bflo(qv[u].w), bfhi(qv[u].w)};
;                     float k[8] = {bflo(kv[u].x), bfhi(kv[u].x), bflo(kv[u].y), bfhi(kv[u].y), bflo(kv[u].z), bfhi(kv[u].z), bflo(kv[u].w), bfhi(kv[u].w)};
;                     float sq = 0.f, sk = 0.f;
; #pragma unroll
;                     for (int j = 0; j < 8; ++j) { sq += q[j] * q[j]; sk += k[j] * k[j]; }
; #pragma unroll
;                     for (int o = 1; o < 8; o <<= 1) { sq += __shfl_xor(sq, o); sk += __shfl_xor(sk, o); }
;                     const float rq = rsqrtf(sq * (1.f / 64.f) + EPS), rk = rsqrtf(sk * (1.f / 64.f) + EPS);
; #pragma unroll
;                     for (int j = 0; j < 8; ++j) { q[j] *= rq * gqv[j]; k[j] *= rk * gkv[j]; }
;                     const size_t dst = ((size_t)(b * 8 + h) * 8192 + s) * 64 + d0;
;                     u32x4 o; o.x = pk2(q[0], q[1]); o.y = pk2(q[2], q[3]); o.z = pk2(q[4], q[5]); o.w = pk2(q[6], q[7]);
;                     *(u32x4*)(WSP(bf16, WS_QN) + dst) = o;
;                     o.x = pk2(k[0], k[1]); o.y = pk2(k[2], k[3]); o.z = pk2(k[4], k[5]); o.w = pk2(k[6], k[7]);
;                     *(u32x4*)(WSP(bf16, WS_KN) + dst) = o;
.LBB0_382:
	s_add_i32 s23, s0, s22
	s_cmp_lt_i32 s23, 0x8000
	s_cselect_b32 s24, s23, s0
	s_ashr_i32 s1, s0, 31
	s_lshl_b64 s[26:27], s[0:1], 12
	s_waitcnt vmcnt(4)
	v_lshl_add_u64 v[8:9], v[18:19], 0, s[26:27]
	s_ashr_i32 s25, s24, 31
	s_lshl_b64 s[24:25], s[24:25], 12
	v_lshl_add_u64 v[8:9], v[18:19], 0, s[24:25]
	global_load_dwordx4 v[12:15], v[8:9], off offset:1024 nt
	s_nop 0
	global_load_dwordx4 v[8:11], v[8:9], off offset:2048 nt
	s_add_i32 s50, s23, s22
	s_cmp_lt_i32 s50, 0x8000
	s_cselect_b32 s50, s50, s0
	s_ashr_i32 s51, s50, 31
	s_lshl_b64 s[48:49], s[50:51], 12
	s_ashr_i32 s0, s0, 10
	s_and_b32 s1, s19, 0x7ffc0
	s_cmpk_gt_i32 s23, 0x7fff
	s_waitcnt vmcnt(5)
	v_mov_b64_e32 v[32:33], v[206:207]
	v_mov_b64_e32 v[34:35], v[208:209]
	v_lshlrev_b32_e32 v44, 16, v32
	v_and_b32_e32 v45, 0xffff0000, v32
	s_waitcnt vmcnt(4)
	v_mov_b64_e32 v[36:37], v[210:211]
	v_mov_b64_e32 v[38:39], v[212:213]
	v_lshlrev_b32_e32 v48, 16, v36
	v_and_b32_e32 v49, 0xffff0000, v36
	v_lshlrev_b32_e32 v40, 16, v35
	v_and_b32_e32 v41, 0xffff0000, v35
	v_lshlrev_b32_e32 v42, 16, v34
	v_and_b32_e32 v43, 0xffff0000, v34
	v_lshlrev_b32_e32 v34, 16, v33
	v_and_b32_e32 v35, 0xffff0000, v33
	v_lshlrev_b32_e32 v32, 16, v39
	v_and_b32_e32 v33, 0xffff0000, v39
	v_lshlrev_b32_e32 v46, 16, v38
	v_and_b32_e32 v47, 0xffff0000, v38
	v_lshlrev_b32_e32 v38, 16, v37
	v_and_b32_e32 v39, 0xffff0000, v37
	v_pk_mul_f32 v[54:55], v[44:45], v[44:45]
	v_pk_mul_f32 v[62:63], v[48:49], v[48:49]
	v_pk_mul_f32 v[52:53], v[34:35], v[34:35]
	v_pk_mul_f32 v[60:61], v[38:39], v[38:39]
	v_mov_b32_e32 v64, v62
	v_mov_b32_e32 v65, v54
	v_mov_b32_e32 v54, v63
	v_mov_b32_e32 v62, v60
	v_mov_b32_e32 v63, v52
	v_pk_add_f32 v[54:55], v[64:65], v[54:55]
	v_pk_mul_f32 v[50:51], v[42:43], v[42:43]
	v_pk_mul_f32 v[58:59], v[46:47], v[46:47]
	v_mov_b32_e32 v52, v61
	v_pk_add_f32 v[54:55], v[62:63], v[54:55]
	v_mov_b32_e32 v60, v58
	v_mov_b32_e32 v61, v50
	v_pk_add_f32 v[52:53], v[52:53], v[54:55]
	v_pk_mul_f32 v[36:37], v[40:41], v[40:41]
	v_pk_mul_f32 v[56:57], v[32:33], v[32:33]
	v_mov_b32_e32 v50, v59
	v_pk_add_f32 v[52:53], v[60:61], v[52:53]
	v_mov_b32_e32 v58, v56
	v_mov_b32_e32 v59, v36
	v_pk_add_f32 v[50:51], v[50:51], v[52:53]
	v_mov_b32_e32 v36, v57
	v_pk_add_f32 v[50:51], v[58:59], v[50:51]
	v_and_or_b32 v52, s0, -8, v17
	v_pk_add_f32 v[36:37], v[36:37], v[50:51]
	ds_bpermute_b32 v51, v29, v37
	ds_bpermute_b32 v50, v29, v36
	v_ashrrev_i32_e32 v53, 31, v52
	v_lshlrev_b64 v[52:53], 19, v[52:53]
	v_or_b32_e32 v52, s1, v52
	v_or_b32_e32 v52, v52, v16
	s_waitcnt lgkmcnt(0)
	v_pk_add_f32 v[36:37], v[36:37], v[50:51]
	ds_bpermute_b32 v51, v30, v37
	ds_bpermute_b32 v50, v30, v36
	v_lshlrev_b64 v[52:53], 1, v[52:53]
	s_waitcnt lgkmcnt(0)
	v_pk_add_f32 v[36:37], v[36:37], v[50:51]
	ds_bpermute_b32 v51, v31, v37
	ds_bpermute_b32 v50, v31, v36
	s_waitcnt lgkmcnt(0)
	v_pk_add_f32 v[36:37], v[36:37], v[50:51]
	s_nop 0
	v_pk_fma_f32 v[36:37], v[36:37], s[8:9], v[28:29] op_sel_hi:[1,0,0]
	s_nop 0
	v_mul_f32_e32 v50, 0x4b800000, v37
	v_cmp_gt_f32_e32 vcc, s18, v37
	v_mul_f32_e32 v51, 0x4b800000, v36
	v_cmp_gt_f32_e64 s[0:1], s18, v36
	v_cndmask_b32_e32 v37, v37, v50, vcc
	v_rsq_f32_e32 v37, v37
	v_cndmask_b32_e64 v36, v36, v51, s[0:1]
	v_rsq_f32_e32 v54, v36
	v_lshl_add_u64 v[50:51], s[4:5], 0, v[52:53]
	v_mul_f32_e32 v36, 0x45800000, v37
	v_cndmask_b32_e32 v36, v37, v36, vcc
	v_mul_f32_e32 v55, 0x45800000, v54
	v_cndmask_b32_e64 v54, v54, v55, s[0:1]
	v_pk_mul_f32 v[56:57], v[20:21], v[36:37] op_sel_hi:[1,0]
	v_pk_mul_f32 v[58:59], v[22:23], v[36:37] op_sel_hi:[1,0]
	v_pk_mul_f32 v[60:61], v[24:25], v[36:37] op_sel_hi:[1,0]
	v_pk_mul_f32 v[36:37], v[26:27], v[36:37] op_sel_hi:[1,0]
	v_pk_mul_f32 v[62:63], v[4:5], v[54:55] op_sel_hi:[1,0]
	v_pk_mul_f32 v[64:65], v[6:7], v[54:55] op_sel_hi:[1,0]
	v_pk_mul_f32 v[66:67], v[0:1], v[54:55] op_sel_hi:[1,0]
	v_pk_mul_f32 v[54:55], v[2:3], v[54:55] op_sel_hi:[1,0]
	v_pk_mul_f32 v[44:45], v[56:57], v[44:45]
	v_pk_mul_f32 v[34:35], v[58:59], v[34:35]
	v_pk_mul_f32 v[42:43], v[60:61], v[42:43]
	v_pk_mul_f32 v[36:37], v[36:37], v[40:41]
	v_pk_mul_f32 v[40:41], v[62:63], v[48:49]
	v_pk_mul_f32 v[38:39], v[64:65], v[38:39]
	v_pk_mul_f32 v[46:47], v[66:67], v[46:47]
	v_pk_mul_f32 v[48:49], v[54:55], v[32:33]
	v_cvt_pk_bf16_f32 v32, v44, v45
	v_cvt_pk_bf16_f32 v33, v34, v35
	v_cvt_pk_bf16_f32 v34, v42, v43
	v_cvt_pk_bf16_f32 v35, v36, v37
	v_lshl_add_u64 v[52:53], s[16:17], 0, v[52:53]
	v_cvt_pk_bf16_f32 v36, v40, v41
	v_cvt_pk_bf16_f32 v37, v38, v39
	v_cvt_pk_bf16_f32 v38, v46, v47
	v_cvt_pk_bf16_f32 v39, v48, v49
	global_store_dwordx4 v[50:51], v[32:35], off
	global_store_dwordx4 v[52:53], v[36:39], off
	v_lshl_add_u64 v[202:203], v[18:19], 0, s[48:49]
	global_load_dwordx4 v[206:209], v[202:203], off offset:1024 nt
	global_load_dwordx4 v[210:213], v[202:203], off offset:2048 nt
	s_cbranch_scc1 .LBB0_381
; #define LAS __attribute__((address_space(3)))
; __device__ __forceinline__ unsigned pk2(float lo, float hi) { f32x2_t v = {lo, hi}; bf16x2_t b = __builtin_convertvector(v, bf16x2_t); return __builtin_bit_cast(unsigned, b); }
; __device__ __forceinline__ void p2_prep(const Ctx& C0) {
;     ...
;             for (int u = 0; u < 2; ++u) {
;                 const int tk = tk0 + u * C.NGW;
;                 if (tk < T) {
;                     const int b = tk >> 13, s = tk & 8191;
;                     float q[8] = {bflo(qv[u].x), bfhi(qv[u].x), bflo(qv[u].y), bfhi(qv[u].y), bflo(qv[u].z), bfhi(qv[u].z), bflo(qv[u].w), bfhi(qv[u].w)};
;                     float k[8] = {bflo(kv[u].x), bfhi(kv[u].x), bflo(kv[u].y), bfhi(kv[u].y), bflo(kv[u].z), bfhi(kv[u].z), bflo(kv[u].w), bfhi(kv[u].w)};
;                     float sq = 0.f, sk = 0.f;
; #pragma unroll
;                     for (int j = 0; j < 8; ++j) { sq += q[j] * q[j]; sk += k[j] * k[j]; }
; #pragma unroll
;                     for (int o = 1; o < 8; o <<= 1) { sq += __shfl_xor(sq, o); sk += __shfl_xor(sk, o); }
;                     const float rq = rsqrtf(sq * (1.f / 64.f) + EPS), rk = rsqrtf(sk * (1.f / 64.f) + EPS);
; #pragma unroll
;                     for (int j = 0; j < 8; ++j) { q[j] *= rq * gqv[j]; k[j] *= rk * gkv[j]; }
;                     const size_t dst = ((size_t)(b * 8 + h) * 8192 + s) * 64 + d0;
;                     u32x4 o; o.x = pk2(q[0], q[1]); o.y = pk2(q[2], q[3]); o.z = pk2(q[4], q[5]); o.w = pk2(q[6], q[7]);
;                     *(u32x4*)(WSP(bf16, WS_QN) + dst) = o;
;                     o.x = pk2(k[0], k[1]); o.y = pk2(k[2], k[3]); o.z = pk2(k[4], k[5]); o.w = pk2(k[6], k[7]);
;                     *(u32x4*)(WSP(bf16, WS_KN) + dst) = o;
;     ...
;         for (int it = C.bid; it < 512; it += C.G) {
;             const int b = it >> 7, s0 = (it & 127) * 64;
; #pragma unroll
;             for (int i = 0; i < 8; ++i) {
;                 const int chunk = tid + 512 * i, row = chunk >> 6, cc = (chunk & 63) * 8;
;                 const u32x4 v = *(const u32x4*)(PROJ + (size_t)(b * 8192 + s0 + row) * 2048 + 1536 + cc);
;                 LAS unsigned* d = (LAS unsigned*)(vt + row * 514 + cc);
	s_waitcnt vmcnt(5)
	v_lshlrev_b32_e32 v42, 16, v12
	v_and_b32_e32 v43, 0xffff0000, v12
	s_waitcnt vmcnt(4)
	v_lshlrev_b32_e32 v54, 16, v8
	v_and_b32_e32 v55, 0xffff0000, v8
	v_lshlrev_b32_e32 v38, 16, v13
	v_and_b32_e32 v39, 0xffff0000, v13
	v_pk_mul_f32 v[12:13], v[42:43], v[42:43]
	v_lshlrev_b32_e32 v50, 16, v9
	v_and_b32_e32 v51, 0xffff0000, v9
	v_pk_mul_f32 v[8:9], v[54:55], v[54:55]
	v_pk_mul_f32 v[40:41], v[38:39], v[38:39]
	v_pk_mul_f32 v[52:53], v[50:51], v[50:51]
	v_mov_b32_e32 v56, v8
	v_mov_b32_e32 v57, v12
	v_mov_b32_e32 v12, v9
	v_lshlrev_b32_e32 v36, 16, v14
	v_and_b32_e32 v37, 0xffff0000, v14
	v_lshlrev_b32_e32 v48, 16, v10
	v_and_b32_e32 v49, 0xffff0000, v10
	v_pk_add_f32 v[8:9], v[56:57], v[12:13]
	v_mov_b32_e32 v12, v52
	v_mov_b32_e32 v13, v40
	v_lshlrev_b32_e32 v32, 16, v15
	v_and_b32_e32 v33, 0xffff0000, v15
	v_pk_mul_f32 v[14:15], v[36:37], v[36:37]
	v_lshlrev_b32_e32 v44, 16, v11
	v_and_b32_e32 v45, 0xffff0000, v11
	v_pk_mul_f32 v[10:11], v[48:49], v[48:49]
	v_pk_add_f32 v[8:9], v[12:13], v[8:9]
	v_mov_b32_e32 v40, v53
	v_pk_add_f32 v[8:9], v[40:41], v[8:9]
	v_mov_b32_e32 v12, v10
	v_mov_b32_e32 v13, v14
	v_pk_mul_f32 v[34:35], v[32:33], v[32:33]
	v_pk_mul_f32 v[46:47], v[44:45], v[44:45]
	v_pk_add_f32 v[8:9], v[12:13], v[8:9]
	v_mov_b32_e32 v14, v11
	v_pk_add_f32 v[8:9], v[14:15], v[8:9]
	v_mov_b32_e32 v10, v46
	v_mov_b32_e32 v11, v34
	v_pk_add_f32 v[8:9], v[10:11], v[8:9]
	v_mov_b32_e32 v34, v47
	v_pk_add_f32 v[8:9], v[34:35], v[8:9]
	ds_bpermute_b32 v11, v29, v9
	ds_bpermute_b32 v10, v29, v8
	s_ashr_i32 s0, s23, 10
	s_waitcnt lgkmcnt(0)
	v_pk_add_f32 v[8:9], v[8:9], v[10:11]
	ds_bpermute_b32 v11, v30, v9
	ds_bpermute_b32 v10, v30, v8
	s_waitcnt lgkmcnt(0)
	v_pk_add_f32 v[8:9], v[8:9], v[10:11]
	ds_bpermute_b32 v11, v31, v9
	ds_bpermute_b32 v10, v31, v8
	s_waitcnt lgkmcnt(0)
	v_pk_add_f32 v[8:9], v[8:9], v[10:11]
	s_nop 0
	v_pk_fma_f32 v[8:9], v[8:9], s[8:9], v[28:29] op_sel_hi:[1,0,0]
	s_nop 0
	v_mul_f32_e32 v10, 0x4b800000, v9
	v_cmp_gt_f32_e32 vcc, s18, v9
	s_nop 1
	v_cndmask_b32_e32 v9, v9, v10, vcc
	v_rsq_f32_e32 v9, v9
	s_nop 0
	v_mul_f32_e32 v10, 0x45800000, v9
	v_cndmask_b32_e32 v10, v9, v10, vcc
	v_mul_f32_e32 v9, 0x4b800000, v8
	v_cmp_gt_f32_e32 vcc, s18, v8
	v_pk_mul_f32 v[12:13], v[20:21], v[10:11] op_sel_hi:[1,0]
	v_pk_mul_f32 v[14:15], v[22:23], v[10:11] op_sel_hi:[1,0]
	v_cndmask_b32_e32 v8, v8, v9, vcc
	v_pk_mul_f32 v[34:35], v[24:25], v[10:11] op_sel_hi:[1,0]
	v_rsq_f32_e32 v11, v8
	v_pk_mul_f32 v[34:35], v[34:35], v[36:37]
	v_pk_mul_f32 v[14:15], v[14:15], v[38:39]
	v_pk_mul_f32 v[12:13], v[12:13], v[42:43]
	v_pk_mul_f32 v[8:9], v[26:27], v[10:11] op_sel_hi:[1,0]
	s_nop 0
	v_pk_mul_f32 v[32:33], v[8:9], v[32:33]
	v_mul_f32_e32 v8, 0x45800000, v11
	v_cndmask_b32_e32 v8, v11, v8, vcc
	v_pk_mul_f32 v[10:11], v[4:5], v[8:9] op_sel_hi:[1,0]
	s_nop 0
	v_pk_mul_f32 v[36:37], v[10:11], v[54:55]
	v_pk_mul_f32 v[10:11], v[6:7], v[8:9] op_sel_hi:[1,0]
	s_nop 0
	v_pk_mul_f32 v[38:39], v[10:11], v[50:51]
	v_pk_mul_f32 v[10:11], v[0:1], v[8:9] op_sel_hi:[1,0]
	v_pk_mul_f32 v[8:9], v[2:3], v[8:9] op_sel_hi:[1,0]
	v_pk_mul_f32 v[40:41], v[10:11], v[48:49]
	v_pk_mul_f32 v[42:43], v[8:9], v[44:45]
	v_and_or_b32 v8, s0, -8, v17
	v_ashrrev_i32_e32 v9, 31, v8
	s_add_i32 s0, s21, s19
	v_lshlrev_b64 v[44:45], 19, v[8:9]
	s_and_b32 s0, s0, 0x7ffc0
	v_or_b32_e32 v8, s0, v44
	v_or_b32_e32 v44, v8, v16
	v_cvt_pk_bf16_f32 v8, v12, v13
	v_lshlrev_b64 v[12:13], 1, v[44:45]
	v_cvt_pk_bf16_f32 v9, v14, v15
	v_cvt_pk_bf16_f32 v10, v34, v35
	v_cvt_pk_bf16_f32 v11, v32, v33
	v_lshl_add_u64 v[14:15], s[4:5], 0, v[12:13]
	global_store_dwordx4 v[14:15], v[8:11], off
	v_lshl_add_u64 v[12:13], s[16:17], 0, v[12:13]
	s_nop 0
	v_cvt_pk_bf16_f32 v8, v36, v37
	v_cvt_pk_bf16_f32 v9, v38, v39
	v_cvt_pk_bf16_f32 v10, v40, v41
	v_cvt_pk_bf16_f32 v11, v42, v43
	global_store_dwordx4 v[12:13], v[8:11], off
	s_branch .LBB0_381
.LBB0_384:
	s_waitcnt vmcnt(0)
	s_sub_i32 s7, s9, s7
	s_add_i32 s7, s7, -1
	s_cmpk_gt_i32 s7, 0x1ff
	s_cbranch_scc1 .LBB0_387
	v_add_u32_e32 v3, 0x200, v182
	v_lshrrev_b32_e32 v6, 6, v3
	v_add_u32_e32 v3, 0x600, v182
	v_lshlrev_b32_e32 v0, 14, v182
	s_waitcnt vmcnt(2)
	v_lshrrev_b32_e32 v8, 6, v3
	v_add_u32_e32 v3, 0xa00, v182
	v_and_b32_e32 v2, 0x3f0, v156
	v_lshrrev_b32_e32 v4, 6, v182
	v_and_b32_e32 v12, 0xfc000, v0
	v_mov_b32_e32 v13, 0
	v_lshrrev_b32_e32 v10, 6, v3
	v_add_u32_e32 v3, 0xe00, v182
	v_add_u32_e32 v23, 0, v2
	v_lshl_add_u64 v[0:1], s[78:79], 0, v[12:13]
	v_mul_u32_u24_e32 v14, 0x404, v4
	v_lshrrev_b32_e32 v12, 6, v3
	s_mov_b64 s[4:5], 0x10000000
	v_mul_u32_u24_e32 v15, 0x404, v6
	v_mul_u32_u24_e32 v17, 0x404, v8
	v_mul_u32_u24_e32 v20, 0x404, v10
	v_mul_u32_u24_e32 v24, 0x404, v12
	v_mov_b32_e32 v3, v13
	v_add_u32_e32 v13, v23, v14
	s_mov_b32 s1, 0
	v_lshl_add_u64 v[0:1], v[0:1], 0, s[4:5]
	v_lshl_add_u32 v5, v182, 1, 0
	v_or_b32_e32 v7, 16, v4
	v_or_b32_e32 v9, 32, v4
	v_or_b32_e32 v11, 48, v4
	v_lshl_add_u64 v[2:3], s[44:45], 0, v[2:3]
	s_lshl_b32 s4, s7, 6
	s_lshl_b32 s5, s9, 6
	v_add_u32_e32 v14, v23, v15
	v_add_u32_e32 v15, 0x4040, v13
	v_add_u32_e32 v16, 0x4048, v13
	v_add_u32_e32 v17, v23, v17
	v_add_u32_e32 v18, 0x8080, v13
	v_add_u32_e32 v19, 0x8088, v13
	v_add_u32_e32 v20, v23, v20
	v_add_u32_e32 v21, 0xc0c0, v13
	v_add_u32_e32 v22, 0xc0c8, v13
	v_add_u32_e32 v23, v23, v24
